# P9 K-loop: last stage (2 LDS-DMA pieces) of each 6-piece load segment is issued from the following MFMA segment; vmcnt 8->6 at those segment ends
# baseline (speedup 1.0000x reference)
; #define PG8_STAGE(bufoff, gbase, voff) do { _Pragma("unroll") for (int _i = 0; _i < 2; ++_i) \
;         __builtin_amdgcn_global_load_lds((const unsigned*)((const char*)(gbase) + (voff)[_i]), (LAS unsigned*)(lds + (bufoff) + ldsw + _i * 8192), 16, 0, 0); } while (0)
; #define PG8_LDA(dst, b, h) do { _Pragma("unroll") for (int m = 0; m < 4; ++m) _Pragma("unroll") for (int k = 0; k < 2; ++k) dst[m][k] = *(const LAS bf16x8*)(lds + PG8_SA(b, h) + aoff + m * 2048 + k * 1024); } while (0)
; #define PG8_LDB(dst, b, h) do { _Pragma("unroll") for (int n = 0; n < 2; ++n) _Pragma("unroll") for (int k = 0; k < 2; ++k) dst[n][k] = *(const LAS bf16x8*)(lds + PG8_SB(b, h) + boff + n * 2048 + k * 1024); } while (0)
; #define PG8_MMA(ai, bj, At, Bt) do { __builtin_amdgcn_s_setprio(1); _Pragma("unroll") for (int m = 0; m < 4; ++m) _Pragma("unroll") for (int n = 0; n < 2; ++n) _Pragma("unroll") for (int k = 0; k < 2; ++k) \
;         acc[ai][bj][m][n] = __builtin_amdgcn_mfma_f32_16x16x32_bf16(Bt[n][k], At[m][k], acc[ai][bj][m][n], 0, 0, 0); __builtin_amdgcn_s_setprio(0); } while (0)
; #define PG8_WAIT_V(n) asm volatile("s_waitcnt vmcnt(" #n ")" ::: "memory")
; #define PG8_WAIT_L(n) asm volatile("s_waitcnt lgkmcnt(" #n ")" ::: "memory")
; #define PG8_BAR __builtin_amdgcn_s_barrier()
; #define PG8_SCHED __builtin_amdgcn_sched_barrier(0)
; template <class Epi, class Sched, bool ALIGN_EPI = true, bool SP2 = true>
; __device__ __forceinline__ void gemm_phase(LAS unsigned char* lds, const Gemm g, const Sched& S, const Epi& E) {
;     ...
;             const char* a1 = cA + (size_t)(t + 1) * kstep;
;             const char* a2 = last ? nA : cA + (size_t)(t + 2) * kstep; const char* b2 = last ? nB : cB + (size_t)(t + 2) * kstep;
;             const char* a3 = a2 + kstep; const char* b3 = b2 + kstep;
;             if (last && has_next) S.a_ready(nxt);
;             if constexpr (SP2) {
;             PG8_LDB(B0, 0, 0); PG8_LDB(B1, 0, 1); PG8_SCHED; PG8_LDA(At, 0, 0); PG8_STAGE(PG8_SA(1, 1), a1 + hstep, voffA);
;             PG8_WAIT_V(8); PG8_WAIT_L(0); PG8_BAR; PG8_MMA(0, 0, At, B0); PG8_MMA(0, 1, At, B1); PG8_BAR; PG8_SCHED;
;             PG8_LDA(At, 0, 1); PG8_STAGE(PG8_SB(0, 0), b2, voffB); PG8_STAGE(PG8_SB(0, 1), b2 + hstep, voffB); PG8_STAGE(PG8_SA(0, 0), a2, voffA);
;             PG8_WAIT_V(8); PG8_WAIT_L(0); PG8_BAR; PG8_MMA(1, 0, At, B0); PG8_MMA(1, 1, At, B1); PG8_BAR; PG8_SCHED;
.LBB0_1810:
	ds_read_b128 v[148:151], v168
	ds_read_b128 v[152:155], v168 offset:1024
	ds_read_b128 v[156:159], v168 offset:2048
	ds_read_b128 v[160:163], v168 offset:3072
	ds_read_b128 v[174:177], v169
	ds_read_b128 v[178:181], v169 offset:1024
	ds_read_b128 v[182:185], v169 offset:2048
	ds_read_b128 v[186:189], v169 offset:3072
	s_add_u32 s30, s4, 0xfff00080
	s_addc_u32 s31, s5, -1
	s_cmp_eq_u32 s56, 60
	s_cselect_b32 s35, s25, s31
	s_cselect_b32 s34, s52, s30
	s_cselect_b32 s31, s23, s55
	s_cselect_b32 s30, s53, s54
	s_add_i32 m0, s40, 0xc000
	ds_read_b128 v[190:193], v170
	ds_read_b128 v[194:197], v170 offset:1024
	ds_read_b128 v[198:201], v170 offset:2048
	ds_read_b128 v[202:205], v170 offset:3072
	ds_read_b128 v[206:209], v170 offset:4096
	ds_read_b128 v[210:213], v170 offset:5120
	ds_read_b128 v[214:217], v170 offset:6144
	ds_read_b128 v[218:221], v170 offset:7168
	global_load_lds_dwordx4 v140, s[4:5]
	s_add_i32 m0, s40, 0xe000
	s_nop 0
	global_load_lds_dwordx4 v142, s[4:5]
	s_waitcnt vmcnt(8)
	s_waitcnt lgkmcnt(0)
	s_setprio 1
	s_barrier
	v_mfma_f32_16x16x32_bf16 v[126:129], v[148:151], v[190:193], v[126:129]
	v_mfma_f32_16x16x32_bf16 v[122:125], v[156:159], v[190:193], v[122:125]
	v_mfma_f32_16x16x32_bf16 v[106:109], v[156:159], v[198:201], v[106:109]
	v_mfma_f32_16x16x32_bf16 v[110:113], v[148:151], v[198:201], v[110:113]
	v_mfma_f32_16x16x32_bf16 v[94:97], v[148:151], v[206:209], v[94:97]
	v_mfma_f32_16x16x32_bf16 v[90:93], v[156:159], v[206:209], v[90:93]
	v_mfma_f32_16x16x32_bf16 v[74:77], v[156:159], v[214:217], v[74:77]
	v_mfma_f32_16x16x32_bf16 v[78:81], v[148:151], v[214:217], v[78:81]
	v_mfma_f32_16x16x32_bf16 v[126:129], v[152:155], v[194:197], v[126:129]
	v_mfma_f32_16x16x32_bf16 v[122:125], v[160:163], v[194:197], v[122:125]
	v_mfma_f32_16x16x32_bf16 v[106:109], v[160:163], v[202:205], v[106:109]
	v_mfma_f32_16x16x32_bf16 v[110:113], v[152:155], v[202:205], v[110:113]
	v_mfma_f32_16x16x32_bf16 v[94:97], v[152:155], v[210:213], v[94:97]
	v_mfma_f32_16x16x32_bf16 v[90:93], v[160:163], v[210:213], v[90:93]
	v_mfma_f32_16x16x32_bf16 v[74:77], v[160:163], v[218:221], v[74:77]
	v_mfma_f32_16x16x32_bf16 v[78:81], v[152:155], v[218:221], v[78:81]
	v_mfma_f32_16x16x32_bf16 v[118:121], v[174:177], v[190:193], v[118:121]
	v_mfma_f32_16x16x32_bf16 v[114:117], v[182:185], v[190:193], v[114:117]
	v_mfma_f32_16x16x32_bf16 v[98:101], v[182:185], v[198:201], v[98:101]
	v_mfma_f32_16x16x32_bf16 v[102:105], v[174:177], v[198:201], v[102:105]
	v_mfma_f32_16x16x32_bf16 v[86:89], v[174:177], v[206:209], v[86:89]
	v_mfma_f32_16x16x32_bf16 v[82:85], v[182:185], v[206:209], v[82:85]
	v_mfma_f32_16x16x32_bf16 v[66:69], v[182:185], v[214:217], v[66:69]
	v_mfma_f32_16x16x32_bf16 v[70:73], v[174:177], v[214:217], v[70:73]
	v_mfma_f32_16x16x32_bf16 v[118:121], v[178:181], v[194:197], v[118:121]
	v_mfma_f32_16x16x32_bf16 v[114:117], v[186:189], v[194:197], v[114:117]
	v_mfma_f32_16x16x32_bf16 v[98:101], v[186:189], v[202:205], v[98:101]
	v_mfma_f32_16x16x32_bf16 v[102:105], v[178:181], v[202:205], v[102:105]
	v_mfma_f32_16x16x32_bf16 v[86:89], v[178:181], v[210:213], v[86:89]
	v_mfma_f32_16x16x32_bf16 v[82:85], v[186:189], v[210:213], v[82:85]
	v_mfma_f32_16x16x32_bf16 v[66:69], v[186:189], v[218:221], v[66:69]
	v_mfma_f32_16x16x32_bf16 v[70:73], v[178:181], v[218:221], v[70:73]
	s_barrier
	s_setprio 0
	s_add_i32 s57, s48, s37
	v_lshl_add_u64 v[164:165], s[30:31], 0, v[134:135]
	s_mov_b32 m0, s57
	ds_read_b128 v[190:193], v170 offset:16384
	ds_read_b128 v[194:197], v170 offset:17408
	ds_read_b128 v[198:201], v170 offset:18432
	ds_read_b128 v[202:205], v170 offset:19456
	ds_read_b128 v[206:209], v170 offset:20480
	ds_read_b128 v[210:213], v170 offset:21504
	ds_read_b128 v[214:217], v170 offset:22528
	ds_read_b128 v[218:221], v170 offset:23552
	global_load_lds_dwordx4 v[164:165], off
	s_add_i32 m0, s57, 0x2000
	s_add_u32 s58, s30, 0x100000
	v_lshl_add_u64 v[222:223], s[30:31], 0, v[130:131]
	s_addc_u32 s59, s31, 0
	s_add_i32 s57, s49, s37
	global_load_lds_dwordx4 v[222:223], off
	s_mov_b32 m0, s57
	v_lshl_add_u64 v[226:227], s[34:35], 0, v[132:133]
	global_load_lds_dwordx4 v134, s[58:59]
	s_add_i32 m0, s57, 0x2000
	s_nop 0
	global_load_lds_dwordx4 v130, s[58:59]
	s_waitcnt vmcnt(6)
	s_waitcnt lgkmcnt(0)
	s_setprio 1
	s_barrier
	v_mfma_f32_16x16x32_bf16 v[62:65], v[148:151], v[190:193], v[62:65]
	v_mfma_f32_16x16x32_bf16 v[58:61], v[156:159], v[190:193], v[58:61]
	v_lshl_add_u64 v[224:225], s[34:35], 0, v[136:137]
	s_mov_b32 m0, s40
	s_nop 0
	global_load_lds_dwordx4 v[224:225], off
	v_mfma_f32_16x16x32_bf16 v[42:45], v[156:159], v[198:201], v[42:45]
	v_mfma_f32_16x16x32_bf16 v[46:49], v[148:151], v[198:201], v[46:49]
	v_mfma_f32_16x16x32_bf16 v[30:33], v[148:151], v[206:209], v[30:33]
	v_mfma_f32_16x16x32_bf16 v[26:29], v[156:159], v[206:209], v[26:29]
	s_mov_b32 m0, s41
	s_nop 0
	global_load_lds_dwordx4 v[226:227], off
	v_mfma_f32_16x16x32_bf16 v[10:13], v[156:159], v[214:217], v[10:13]
	v_mfma_f32_16x16x32_bf16 v[14:17], v[148:151], v[214:217], v[14:17]
	v_mfma_f32_16x16x32_bf16 v[62:65], v[152:155], v[194:197], v[62:65]
	v_mfma_f32_16x16x32_bf16 v[58:61], v[160:163], v[194:197], v[58:61]
	v_mfma_f32_16x16x32_bf16 v[42:45], v[160:163], v[202:205], v[42:45]
	v_mfma_f32_16x16x32_bf16 v[46:49], v[152:155], v[202:205], v[46:49]
	v_mfma_f32_16x16x32_bf16 v[30:33], v[152:155], v[210:213], v[30:33]
	v_mfma_f32_16x16x32_bf16 v[26:29], v[160:163], v[210:213], v[26:29]
	v_mfma_f32_16x16x32_bf16 v[10:13], v[160:163], v[218:221], v[10:13]
	v_mfma_f32_16x16x32_bf16 v[14:17], v[152:155], v[218:221], v[14:17]
	v_mfma_f32_16x16x32_bf16 v[54:57], v[174:177], v[190:193], v[54:57]
	v_mfma_f32_16x16x32_bf16 v[50:53], v[182:185], v[190:193], v[50:53]
	v_mfma_f32_16x16x32_bf16 v[34:37], v[182:185], v[198:201], v[34:37]
	v_mfma_f32_16x16x32_bf16 v[38:41], v[174:177], v[198:201], v[38:41]
	v_mfma_f32_16x16x32_bf16 v[22:25], v[174:177], v[206:209], v[22:25]
	v_mfma_f32_16x16x32_bf16 v[18:21], v[182:185], v[206:209], v[18:21]
	v_mfma_f32_16x16x32_bf16 v[2:5], v[182:185], v[214:217], v[2:5]
	v_mfma_f32_16x16x32_bf16 v[6:9], v[174:177], v[214:217], v[6:9]
	v_mfma_f32_16x16x32_bf16 v[54:57], v[178:181], v[194:197], v[54:57]
	v_mfma_f32_16x16x32_bf16 v[50:53], v[186:189], v[194:197], v[50:53]
	v_mfma_f32_16x16x32_bf16 v[34:37], v[186:189], v[202:205], v[34:37]
	v_mfma_f32_16x16x32_bf16 v[38:41], v[178:181], v[202:205], v[38:41]
	v_mfma_f32_16x16x32_bf16 v[22:25], v[178:181], v[210:213], v[22:25]
	v_mfma_f32_16x16x32_bf16 v[18:21], v[186:189], v[210:213], v[18:21]
	v_mfma_f32_16x16x32_bf16 v[2:5], v[186:189], v[218:221], v[2:5]
	v_mfma_f32_16x16x32_bf16 v[6:9], v[178:181], v[218:221], v[6:9]
	s_barrier
; #define PG8_STAGE(bufoff, gbase, voff) do { _Pragma("unroll") for (int _i = 0; _i < 2; ++_i) \
;         __builtin_amdgcn_global_load_lds((const unsigned*)((const char*)(gbase) + (voff)[_i]), (LAS unsigned*)(lds + (bufoff) + ldsw + _i * 8192), 16, 0, 0); } while (0)
; #define PG8_LDA(dst, b, h) do { _Pragma("unroll") for (int m = 0; m < 4; ++m) _Pragma("unroll") for (int k = 0; k < 2; ++k) dst[m][k] = *(const LAS bf16x8*)(lds + PG8_SA(b, h) + aoff + m * 2048 + k * 1024); } while (0)
; #define PG8_LDB(dst, b, h) do { _Pragma("unroll") for (int n = 0; n < 2; ++n) _Pragma("unroll") for (int k = 0; k < 2; ++k) dst[n][k] = *(const LAS bf16x8*)(lds + PG8_SB(b, h) + boff + n * 2048 + k * 1024); } while (0)
; #define PG8_MMA(ai, bj, At, Bt) do { __builtin_amdgcn_s_setprio(1); _Pragma("unroll") for (int m = 0; m < 4; ++m) _Pragma("unroll") for (int n = 0; n < 2; ++n) _Pragma("unroll") for (int k = 0; k < 2; ++k) \
;         acc[ai][bj][m][n] = __builtin_amdgcn_mfma_f32_16x16x32_bf16(Bt[n][k], At[m][k], acc[ai][bj][m][n], 0, 0, 0); __builtin_amdgcn_s_setprio(0); } while (0)
; #define PG8_WAIT_V(n) asm volatile("s_waitcnt vmcnt(" #n ")" ::: "memory")
; #define PG8_WAIT_L(n) asm volatile("s_waitcnt lgkmcnt(" #n ")" ::: "memory")
; #define PG8_BAR __builtin_amdgcn_s_barrier()
; #define PG8_SCHED __builtin_amdgcn_sched_barrier(0)
; template <class Epi, class Sched, bool ALIGN_EPI = true, bool SP2 = true>
; __device__ __forceinline__ void gemm_phase(LAS unsigned char* lds, const Gemm g, const Sched& S, const Epi& E) {
;     ...
;         for (int t = 0; t < nt; t += 2) {
;     ...
;             PG8_LDB(B0, 1, 0); PG8_LDB(B1, 1, 1); PG8_SCHED; PG8_LDA(At, 1, 0); PG8_STAGE(PG8_SA(0, 1), a2 + hstep, voffA);
;             PG8_WAIT_V(8); PG8_WAIT_L(0); PG8_BAR; PG8_MMA(0, 0, At, B0); PG8_MMA(0, 1, At, B1); PG8_BAR; PG8_SCHED;
;             PG8_LDA(At, 1, 1); PG8_STAGE(PG8_SB(1, 0), b3, voffB); PG8_STAGE(PG8_SB(1, 1), b3 + hstep, voffB); PG8_STAGE(PG8_SA(1, 0), a3, voffA);
;             PG8_WAIT_V(8); PG8_WAIT_L(0); PG8_BAR; PG8_MMA(1, 0, At, B0); PG8_MMA(1, 1, At, B1); PG8_BAR; PG8_SCHED;
	s_setprio 0
	s_add_i32 s57, 0, 0x18000
	s_add_i32 s58, 0, 0x1c000
	v_add_u32_e32 v160, s57, v167
	v_add_u32_e32 v173, s58, v167
	ds_read_b128 v[148:151], v160
	ds_read_b128 v[152:155], v160 offset:1024
	ds_read_b128 v[156:159], v160 offset:2048
	ds_read_b128 v[160:163], v160 offset:3072
	ds_read_b128 v[174:177], v173
	ds_read_b128 v[178:181], v173 offset:1024
	ds_read_b128 v[182:185], v173 offset:2048
	ds_read_b128 v[186:189], v173 offset:3072
	s_add_u32 s34, s34, 0x100000
	s_addc_u32 s35, s35, 0
	s_mov_b32 m0, s42
	ds_read_b128 v[190:193], v170 offset:32768
	ds_read_b128 v[194:197], v170 offset:33792
	ds_read_b128 v[198:201], v170 offset:34816
	ds_read_b128 v[202:205], v170 offset:35840
	ds_read_b128 v[206:209], v170 offset:36864
	ds_read_b128 v[210:213], v170 offset:37888
	ds_read_b128 v[214:217], v170 offset:38912
	ds_read_b128 v[218:221], v170 offset:39936
	global_load_lds_dwordx4 v136, s[34:35]
	s_mov_b32 m0, s43
	s_nop 0
	global_load_lds_dwordx4 v132, s[34:35]
	s_waitcnt vmcnt(8)
	s_waitcnt lgkmcnt(0)
	s_setprio 1
	s_barrier
	v_mfma_f32_16x16x32_bf16 v[126:129], v[148:151], v[190:193], v[126:129]
	v_mfma_f32_16x16x32_bf16 v[122:125], v[156:159], v[190:193], v[122:125]
	v_mfma_f32_16x16x32_bf16 v[106:109], v[156:159], v[198:201], v[106:109]
	v_mfma_f32_16x16x32_bf16 v[110:113], v[148:151], v[198:201], v[110:113]
	v_mfma_f32_16x16x32_bf16 v[94:97], v[148:151], v[206:209], v[94:97]
	v_mfma_f32_16x16x32_bf16 v[90:93], v[156:159], v[206:209], v[90:93]
	v_mfma_f32_16x16x32_bf16 v[74:77], v[156:159], v[214:217], v[74:77]
	v_mfma_f32_16x16x32_bf16 v[78:81], v[148:151], v[214:217], v[78:81]
	v_mfma_f32_16x16x32_bf16 v[126:129], v[152:155], v[194:197], v[126:129]
	v_mfma_f32_16x16x32_bf16 v[122:125], v[160:163], v[194:197], v[122:125]
	v_mfma_f32_16x16x32_bf16 v[106:109], v[160:163], v[202:205], v[106:109]
	v_mfma_f32_16x16x32_bf16 v[110:113], v[152:155], v[202:205], v[110:113]
	v_mfma_f32_16x16x32_bf16 v[94:97], v[152:155], v[210:213], v[94:97]
	v_mfma_f32_16x16x32_bf16 v[90:93], v[160:163], v[210:213], v[90:93]
	v_mfma_f32_16x16x32_bf16 v[74:77], v[160:163], v[218:221], v[74:77]
	v_mfma_f32_16x16x32_bf16 v[78:81], v[152:155], v[218:221], v[78:81]
	v_mfma_f32_16x16x32_bf16 v[118:121], v[174:177], v[190:193], v[118:121]
	v_mfma_f32_16x16x32_bf16 v[114:117], v[182:185], v[190:193], v[114:117]
	v_mfma_f32_16x16x32_bf16 v[98:101], v[182:185], v[198:201], v[98:101]
	v_mfma_f32_16x16x32_bf16 v[102:105], v[174:177], v[198:201], v[102:105]
	v_mfma_f32_16x16x32_bf16 v[86:89], v[174:177], v[206:209], v[86:89]
	v_mfma_f32_16x16x32_bf16 v[82:85], v[182:185], v[206:209], v[82:85]
	v_mfma_f32_16x16x32_bf16 v[66:69], v[182:185], v[214:217], v[66:69]
	v_mfma_f32_16x16x32_bf16 v[70:73], v[174:177], v[214:217], v[70:73]
	v_mfma_f32_16x16x32_bf16 v[118:121], v[178:181], v[194:197], v[118:121]
	v_mfma_f32_16x16x32_bf16 v[114:117], v[186:189], v[194:197], v[114:117]
	v_mfma_f32_16x16x32_bf16 v[98:101], v[186:189], v[202:205], v[98:101]
	v_mfma_f32_16x16x32_bf16 v[102:105], v[178:181], v[202:205], v[102:105]
	v_mfma_f32_16x16x32_bf16 v[86:89], v[178:181], v[210:213], v[86:89]
	v_mfma_f32_16x16x32_bf16 v[82:85], v[186:189], v[210:213], v[82:85]
	v_mfma_f32_16x16x32_bf16 v[66:69], v[186:189], v[218:221], v[66:69]
	v_mfma_f32_16x16x32_bf16 v[70:73], v[178:181], v[218:221], v[70:73]
	s_barrier
	s_setprio 0
	s_add_i32 s34, s57, s37
	v_lshl_add_u64 v[164:165], v[164:165], 0, s[18:19]
	s_mov_b32 m0, s34
	ds_read_b128 v[190:193], v170 offset:49152
	ds_read_b128 v[194:197], v170 offset:50176
	ds_read_b128 v[198:201], v170 offset:51200
	ds_read_b128 v[202:205], v170 offset:52224
	ds_read_b128 v[206:209], v170 offset:53248
	ds_read_b128 v[210:213], v170 offset:54272
	ds_read_b128 v[214:217], v170 offset:55296
	ds_read_b128 v[218:221], v170 offset:56320
	global_load_lds_dwordx4 v[164:165], off
	s_add_i32 m0, s34, 0x2000
	s_add_u32 s30, s30, 0x100080
	v_lshl_add_u64 v[164:165], v[222:223], 0, s[18:19]
	s_addc_u32 s31, s31, 0
	s_add_i32 s34, s58, s37
	global_load_lds_dwordx4 v[164:165], off
	s_mov_b32 m0, s34
	s_nop 0
	global_load_lds_dwordx4 v134, s[30:31]
	s_add_i32 m0, s34, 0x2000
	s_nop 0
	global_load_lds_dwordx4 v130, s[30:31]
	s_waitcnt vmcnt(6)
	s_waitcnt lgkmcnt(0)
	s_setprio 1
	s_barrier
	v_mfma_f32_16x16x32_bf16 v[62:65], v[148:151], v[190:193], v[62:65]
	v_mfma_f32_16x16x32_bf16 v[58:61], v[156:159], v[190:193], v[58:61]
	v_lshl_add_u64 v[164:165], v[224:225], 0, s[18:19]
	s_mov_b32 m0, s45
	s_nop 0
	global_load_lds_dwordx4 v[164:165], off
	v_mfma_f32_16x16x32_bf16 v[42:45], v[156:159], v[198:201], v[42:45]
	v_mfma_f32_16x16x32_bf16 v[46:49], v[148:151], v[198:201], v[46:49]
	v_mfma_f32_16x16x32_bf16 v[30:33], v[148:151], v[206:209], v[30:33]
	v_mfma_f32_16x16x32_bf16 v[26:29], v[156:159], v[206:209], v[26:29]
	v_lshl_add_u64 v[164:165], v[226:227], 0, s[18:19]
	s_mov_b32 m0, s46
	s_nop 0
	global_load_lds_dwordx4 v[164:165], off
	v_mfma_f32_16x16x32_bf16 v[10:13], v[156:159], v[214:217], v[10:13]
	v_mfma_f32_16x16x32_bf16 v[14:17], v[148:151], v[214:217], v[14:17]
	v_mfma_f32_16x16x32_bf16 v[62:65], v[152:155], v[194:197], v[62:65]
	v_mfma_f32_16x16x32_bf16 v[58:61], v[160:163], v[194:197], v[58:61]
	v_mfma_f32_16x16x32_bf16 v[42:45], v[160:163], v[202:205], v[42:45]
	v_mfma_f32_16x16x32_bf16 v[46:49], v[152:155], v[202:205], v[46:49]
	v_mfma_f32_16x16x32_bf16 v[30:33], v[152:155], v[210:213], v[30:33]
	v_mfma_f32_16x16x32_bf16 v[26:29], v[160:163], v[210:213], v[26:29]
	v_mfma_f32_16x16x32_bf16 v[10:13], v[160:163], v[218:221], v[10:13]
	v_mfma_f32_16x16x32_bf16 v[14:17], v[152:155], v[218:221], v[14:17]
	v_mfma_f32_16x16x32_bf16 v[54:57], v[174:177], v[190:193], v[54:57]
	v_mfma_f32_16x16x32_bf16 v[50:53], v[182:185], v[190:193], v[50:53]
	v_mfma_f32_16x16x32_bf16 v[34:37], v[182:185], v[198:201], v[34:37]
	v_mfma_f32_16x16x32_bf16 v[38:41], v[174:177], v[198:201], v[38:41]
	v_mfma_f32_16x16x32_bf16 v[22:25], v[174:177], v[206:209], v[22:25]
	v_mfma_f32_16x16x32_bf16 v[18:21], v[182:185], v[206:209], v[18:21]
	v_mfma_f32_16x16x32_bf16 v[2:5], v[182:185], v[214:217], v[2:5]
	v_mfma_f32_16x16x32_bf16 v[6:9], v[174:177], v[214:217], v[6:9]
	v_mfma_f32_16x16x32_bf16 v[54:57], v[178:181], v[194:197], v[54:57]
	v_mfma_f32_16x16x32_bf16 v[50:53], v[186:189], v[194:197], v[50:53]
	v_mfma_f32_16x16x32_bf16 v[34:37], v[186:189], v[202:205], v[34:37]
	v_mfma_f32_16x16x32_bf16 v[38:41], v[178:181], v[202:205], v[38:41]
	v_mfma_f32_16x16x32_bf16 v[22:25], v[178:181], v[210:213], v[22:25]
	v_mfma_f32_16x16x32_bf16 v[18:21], v[186:189], v[210:213], v[18:21]
	v_mfma_f32_16x16x32_bf16 v[2:5], v[186:189], v[218:221], v[2:5]
	v_mfma_f32_16x16x32_bf16 v[6:9], v[178:181], v[218:221], v[6:9]
	s_barrier
	s_setprio 0
	s_add_i32 s56, s56, 2
	s_add_u32 s4, s4, 0x100
	s_addc_u32 s5, s5, 0
	s_add_u32 s54, s54, 0x100
	s_addc_u32 s55, s55, 0
	s_cmp_gt_u32 s56, 61
	s_cbranch_scc0 .LBB0_1810
	s_and_b64 vcc, exec, s[20:21]
	s_cbranch_vccz .LBB0_1813
	s_barrier
